# NSA: drop mid-compute vmcnt0 fences before V transpose reads; conversion single-wait + column-major tile order; QKV epilogue LDS gains + cos-sin prefetch
# speedup vs baseline: 1.0301x; 1.0072x over previous
.LBB0_33:
	s_mul_i32 s0, s17, 40
	v_readlane_b32 s4, v253, 2
	s_mul_hi_u32 s1, s17, 40
	v_readlane_b32 s5, v253, 3
	s_add_u32 s0, s4, s0
	s_addc_u32 s1, s5, s1
	s_load_dwordx4 s[4:7], s[0:1], 0xd8
	s_waitcnt lgkmcnt(0)
	s_ashr_i32 s20, s6, 6
	s_ashr_i32 s7, s7, 7
	s_mov_b32 s38, s7
	s_mul_i32 s7, s7, s20
	s_cmp_ge_i32 s16, s7
	s_cbranch_scc1 .LBB0_32
	s_abs_i32 s26, s38
	v_cvt_f32_u32_e32 v2, s26
	s_load_dword s27, s[0:1], 0xe8
	s_load_dwordx4 s[8:11], s[0:1], 0xc8
	s_lshl_b32 s0, s20, 6
	s_sub_i32 s1, 0, s26
	v_rcp_iflag_f32_e32 v2, v2
	s_sub_i32 s30, 0, s0
	s_ashr_i32 s28, s38, 31
	s_mov_b32 s29, s19
	v_mul_f32_e32 v2, 0x4f7ffffe, v2
	v_cvt_u32_f32_e32 v2, v2
	s_mov_b32 s33, s16
	v_readfirstlane_b32 s0, v2
	s_mul_i32 s1, s1, s0
	s_mul_hi_u32 s1, s0, s1
	s_add_i32 s31, s0, s1
	s_branch .LBB0_36

.LBB0_36:
	s_abs_i32 s1, s33
	s_mul_hi_u32 s20, s1, s31
	s_mul_i32 s21, s20, s26
	s_ashr_i32 s0, s33, 31
	s_sub_i32 s1, s1, s21
	s_xor_b32 s0, s0, s28
	s_add_i32 s21, s20, 1
	s_sub_i32 s34, s1, s26
	s_cmp_ge_u32 s1, s26
	s_cselect_b32 s20, s21, s20
	s_cselect_b32 s1, s34, s1
	s_add_i32 s21, s20, 1
	s_cmp_ge_u32 s1, s26
	s_cselect_b32 s1, s21, s20
	s_xor_b32 s1, s1, s0
	s_sub_i32 s39, s1, s0
	s_mul_i32 s35, s39, s38
	s_sub_i32 s35, s33, s35
	s_lshl_b32 s34, s35, 7
	s_and_b32 s0, s34, 0xffffff00
	s_and_b32 s20, s35, 1
	v_or_b32_e32 v2, s0, v40
	s_lshl_b32 s0, s20, 5
	s_waitcnt lgkmcnt(0)
	s_cmp_lt_i32 s27, 1
	v_or3_b32 v3, v2, s0, v41
	s_cbranch_scc1 .LBB0_41
	s_cmp_gt_i32 s27, 1
	s_cbranch_scc0 .LBB0_42
	s_cmp_eq_u32 s27, 2
	s_mov_b64 s[0:1], -1
	s_cbranch_scc0 .LBB0_40
	s_ashr_i32 s0, s34, 1
	s_mulk_i32 s20, 0xb00
	s_and_b32 s0, s0, 0xffffff80
	s_add_i32 s0, s0, s20
	v_or_b32_e32 v2, s0, v39
	s_mov_b64 s[0:1], 0

.LBB0_48:
	s_lshl_b32 s20, s39, 6
	v_add_u32_e32 v15, s20, v38
	v_cmp_gt_i32_e32 vcc, s4, v2
	v_ashrrev_i32_e32 v3, 31, v2
	v_lshl_add_u64 v[36:37], v[2:3], 2, s[8:9]
	v_add_u32_e32 v11, 16, v15
	v_add_u32_e32 v16, 32, v15
	v_add_u32_e32 v35, 48, v15
	v_mov_b32_e32 v18, 0
	v_mov_b32_e32 v19, 0
	v_mov_b32_e32 v20, 0
	v_mov_b32_e32 v21, 0
	v_mov_b32_e32 v22, 0
	v_mov_b32_e32 v23, 0
	v_mov_b32_e32 v24, 0
	v_mov_b32_e32 v25, 0
	v_mov_b32_e32 v26, 0
	v_mov_b32_e32 v27, 0
	v_mov_b32_e32 v28, 0
	v_mov_b32_e32 v29, 0
	v_mov_b32_e32 v30, 0
	v_mov_b32_e32 v31, 0
	v_mov_b32_e32 v32, 0
	v_mov_b32_e32 v33, 0
	v_mad_i64_i32 v[2:3], s[40:41], v15, s4, 0
	v_mad_i64_i32 v[4:5], s[40:41], v11, s4, 0
	v_mad_i64_i32 v[6:7], s[40:41], v16, s4, 0
	v_mad_i64_i32 v[8:9], s[40:41], v35, s4, 0
	v_lshl_add_u64 v[2:3], v[2:3], 2, v[36:37]
	v_lshl_add_u64 v[4:5], v[4:5], 2, v[36:37]
	v_lshl_add_u64 v[6:7], v[6:7], 2, v[36:37]
	v_lshl_add_u64 v[8:9], v[8:9], 2, v[36:37]
	s_mov_b64 s[36:37], exec
	v_cmp_gt_i32_e64 s[0:1], s5, v15
	s_nop 0
	s_and_b64 s[0:1], s[0:1], vcc
	s_and_b64 exec, s[36:37], s[0:1]
	global_load_dwordx4 v[18:21], v[2:3], off
	s_mov_b64 exec, s[36:37]
	v_cmp_gt_i32_e64 s[0:1], s5, v11
	s_nop 0
	s_and_b64 s[0:1], s[0:1], vcc
	s_and_b64 exec, s[36:37], s[0:1]
	global_load_dwordx4 v[22:25], v[4:5], off
	s_mov_b64 exec, s[36:37]
	v_cmp_gt_i32_e64 s[0:1], s5, v16
	s_nop 0
	s_and_b64 s[0:1], s[0:1], vcc
	s_and_b64 exec, s[36:37], s[0:1]
	global_load_dwordx4 v[26:29], v[6:7], off
	s_mov_b64 exec, s[36:37]
	v_cmp_gt_i32_e64 s[0:1], s5, v35
	s_nop 0
	s_and_b64 s[0:1], s[0:1], vcc
	s_and_b64 exec, s[36:37], s[0:1]
	global_load_dwordx4 v[30:33], v[8:9], off
	s_mov_b64 exec, s[36:37]
	s_mov_b64 s[0:1], 0
	v_mov_b32_e32 v15, v14
	s_waitcnt vmcnt(0)
	s_branch .LBB0_35

.LBB0_266:
	s_or_b64 exec, exec, s[0:1]
	v_add_u32_e32 v15, s25, v8
	v_cvt_pk_bf16_f32 v63, v64, v65
	v_cvt_pk_bf16_f32 v64, v66, v67
	v_cvt_pk_bf16_f32 v65, v68, v69
	s_nop 0
	ds_read_b64_tr_b16 v[66:67], v15 offset:18432
	ds_read_b64_tr_b16 v[68:69], v15 offset:19584
	v_cvt_pk_bf16_f32 v62, v13, v49
	v_cvt_pk_bf16_f32 v56, v56, v57
	v_cvt_pk_bf16_f32 v57, v58, v59
	s_waitcnt lgkmcnt(0)
	v_mfma_f32_32x32x16_bf16 v[32:47], v[66:69], v[62:65], v[32:47]
	ds_read_b64_tr_b16 v[66:67], v15 offset:18496
	ds_read_b64_tr_b16 v[68:69], v15 offset:19648
	v_cvt_pk_bf16_f32 v58, v60, v6
	v_cvt_pk_bf16_f32 v59, v7, v61
	v_cvt_pk_bf16_f32 v10, v9, v10
	v_cvt_pk_bf16_f32 v11, v11, v12
	v_cvt_pk_bf16_f32 v12, v14, v48
	v_cvt_pk_bf16_f32 v13, v50, v53
	s_waitcnt lgkmcnt(0)
	v_mfma_f32_32x32x16_bf16 v[16:31], v[66:69], v[62:65], v[16:31]
	ds_read_b64_tr_b16 v[60:61], v15 offset:20736
	ds_read_b64_tr_b16 v[62:63], v15 offset:21888
	s_waitcnt lgkmcnt(0)
	v_mfma_f32_32x32x16_bf16 v[32:47], v[60:63], v[56:59], v[32:47]
	ds_read_b64_tr_b16 v[60:61], v15 offset:20800
	ds_read_b64_tr_b16 v[62:63], v15 offset:21952
	s_waitcnt lgkmcnt(0)
	v_mfma_f32_32x32x16_bf16 v[16:31], v[60:63], v[56:59], v[16:31]
	ds_read_b64_tr_b16 v[56:57], v15 offset:23040
	ds_read_b64_tr_b16 v[58:59], v15 offset:24192
	s_waitcnt lgkmcnt(0)
	v_mfma_f32_32x32x16_bf16 v[32:47], v[56:59], v[10:13], v[32:47]
	ds_read_b64_tr_b16 v[56:57], v15 offset:23104
	ds_read_b64_tr_b16 v[58:59], v15 offset:24256
	s_waitcnt lgkmcnt(0)
	v_mfma_f32_32x32x16_bf16 v[16:31], v[56:59], v[10:13], v[16:31]
	v_cvt_pk_bf16_f32 v12, v1, v4
	v_cvt_pk_bf16_f32 v13, v5, v2
	ds_read_b64_tr_b16 v[4:5], v15 offset:25344
	ds_read_b64_tr_b16 v[6:7], v15 offset:26496
	v_cvt_pk_bf16_f32 v10, v51, v52
	v_cvt_pk_bf16_f32 v11, v54, v55
	s_waitcnt lgkmcnt(0)
	s_nop 0
	v_mfma_f32_32x32x16_bf16 v[32:47], v[4:7], v[10:13], v[32:47]
	ds_read_b64_tr_b16 v[4:5], v15 offset:25408
	ds_read_b64_tr_b16 v[6:7], v15 offset:26560
	s_waitcnt lgkmcnt(0)
	v_mfma_f32_32x32x16_bf16 v[16:31], v[4:7], v[10:13], v[16:31]

.LBB0_361:
	s_or_b64 exec, exec, s[66:67]
	v_exp_f32_e32 v142, v68
	v_add3_u32 v1, s70, v154, v155
	s_nop 0
	ds_read_b64_tr_b16 v[70:71], v1 offset:18432
	ds_read_b64_tr_b16 v[72:73], v1 offset:19584
	v_cvt_pk_bf16_f32 v68, v58, v59
	v_pk_add_f32 v[66:67], v[142:143], v[66:67]
	v_cvt_pk_bf16_f32 v69, v62, v63
	v_add_f32_e32 v143, v66, v67
	v_cvt_pk_bf16_f32 v66, v38, v39
	v_cvt_pk_bf16_f32 v67, v52, v53
	v_cvt_pk_bf16_f32 v34, v34, v35
	v_cvt_pk_bf16_f32 v35, v36, v37
	s_waitcnt lgkmcnt(0)
	v_mfma_f32_32x32x16_bf16 v[18:33], v[70:73], v[66:69], v[18:33]
	ds_read_b64_tr_b16 v[70:71], v1 offset:18496
	ds_read_b64_tr_b16 v[72:73], v1 offset:19648
	v_cvt_pk_bf16_f32 v36, v40, v41
	v_cvt_pk_bf16_f32 v37, v60, v61
	s_waitcnt lgkmcnt(0)
	v_mfma_f32_32x32x16_bf16 v[2:17], v[70:73], v[66:69], v[2:17]
	v_cvt_pk_bf16_f32 v68, v50, v51
	ds_read_b64_tr_b16 v[50:51], v1 offset:20736
	ds_read_b64_tr_b16 v[52:53], v1 offset:21888
	v_cvt_pk_bf16_f32 v66, v42, v43
	v_cvt_pk_bf16_f32 v67, v46, v47
	v_cvt_pk_bf16_f32 v69, v56, v57
	s_waitcnt lgkmcnt(0)
	s_nop 0
	v_mfma_f32_32x32x16_bf16 v[18:33], v[50:53], v[66:69], v[18:33]
	ds_read_b64_tr_b16 v[50:51], v1 offset:20800
	ds_read_b64_tr_b16 v[52:53], v1 offset:21952
	ds_read_b64_tr_b16 v[38:39], v1 offset:23040
	ds_read_b64_tr_b16 v[40:41], v1 offset:24192
	s_waitcnt lgkmcnt(2)
	v_mfma_f32_32x32x16_bf16 v[2:17], v[50:53], v[66:69], v[2:17]
	s_waitcnt lgkmcnt(0)
	v_mfma_f32_32x32x16_bf16 v[18:33], v[38:41], v[34:37], v[18:33]
	ds_read_b64_tr_b16 v[38:39], v1 offset:23104
	ds_read_b64_tr_b16 v[40:41], v1 offset:24256
	s_waitcnt lgkmcnt(0)
	v_mfma_f32_32x32x16_bf16 v[2:17], v[38:41], v[34:37], v[2:17]
	ds_read_b64_tr_b16 v[38:39], v1 offset:25344
	ds_read_b64_tr_b16 v[40:41], v1 offset:26496
	v_cvt_pk_bf16_f32 v34, v44, v45
	v_cvt_pk_bf16_f32 v35, v48, v49
	v_cvt_pk_bf16_f32 v36, v54, v55
	v_cvt_pk_bf16_f32 v37, v64, v142
	s_waitcnt lgkmcnt(0)
	s_nop 0
	v_mfma_f32_32x32x16_bf16 v[18:33], v[38:41], v[34:37], v[18:33]
	ds_read_b64_tr_b16 v[38:39], v1 offset:25408
	ds_read_b64_tr_b16 v[40:41], v1 offset:26560
	s_waitcnt lgkmcnt(0)
	v_mfma_f32_32x32x16_bf16 v[2:17], v[38:41], v[34:37], v[2:17]

.LBB0_368:
	s_or_b64 exec, exec, s[50:51]
	v_exp_f32_e32 v1, v179
	v_cvt_pk_bf16_f32 v34, v34, v35
	v_cvt_pk_bf16_f32 v35, v36, v37
	v_cvt_pk_bf16_f32 v36, v38, v39
	v_add_f32_e32 v69, v1, v144
	v_add_f32_e32 v143, v69, v145
	v_add3_u32 v69, s90, v154, v155
	s_nop 0
	ds_read_b64_tr_b16 v[180:181], v69 offset:18432
	ds_read_b64_tr_b16 v[182:183], v69 offset:19584
	v_cvt_pk_bf16_f32 v37, v42, v43
	s_waitcnt lgkmcnt(0)
	s_nop 0
	v_mfma_f32_32x32x16_bf16 v[18:33], v[180:183], v[34:37], v[18:33]
	ds_read_b64_tr_b16 v[180:181], v69 offset:18496
	ds_read_b64_tr_b16 v[182:183], v69 offset:19648
	s_waitcnt lgkmcnt(0)
	v_mfma_f32_32x32x16_bf16 v[2:17], v[180:183], v[34:37], v[2:17]
	v_cvt_pk_bf16_f32 v34, v40, v41
	ds_read_b64_tr_b16 v[38:39], v69 offset:20736
	ds_read_b64_tr_b16 v[40:41], v69 offset:21888
	v_cvt_pk_bf16_f32 v35, v48, v49
	v_cvt_pk_bf16_f32 v36, v50, v51
	v_cvt_pk_bf16_f32 v37, v52, v53
	s_waitcnt lgkmcnt(0)
	s_nop 0
	v_mfma_f32_32x32x16_bf16 v[18:33], v[38:41], v[34:37], v[18:33]
	ds_read_b64_tr_b16 v[38:39], v69 offset:20800
	ds_read_b64_tr_b16 v[40:41], v69 offset:21952
	s_waitcnt lgkmcnt(0)
	v_mfma_f32_32x32x16_bf16 v[2:17], v[38:41], v[34:37], v[2:17]
	ds_read_b64_tr_b16 v[38:39], v69 offset:23040
	ds_read_b64_tr_b16 v[40:41], v69 offset:24192
	v_cvt_pk_bf16_f32 v34, v44, v45
	v_cvt_pk_bf16_f32 v35, v46, v47
	v_cvt_pk_bf16_f32 v36, v54, v55
	v_cvt_pk_bf16_f32 v37, v56, v57
	s_waitcnt lgkmcnt(0)
	s_nop 0
	v_mfma_f32_32x32x16_bf16 v[18:33], v[38:41], v[34:37], v[18:33]
	ds_read_b64_tr_b16 v[38:39], v69 offset:23104
	ds_read_b64_tr_b16 v[40:41], v69 offset:24256
	s_waitcnt lgkmcnt(0)
	v_mfma_f32_32x32x16_bf16 v[2:17], v[38:41], v[34:37], v[2:17]
	ds_read_b64_tr_b16 v[38:39], v69 offset:25344
	ds_read_b64_tr_b16 v[40:41], v69 offset:26496
	v_cvt_pk_bf16_f32 v34, v58, v59
	v_cvt_pk_bf16_f32 v35, v60, v61
	v_cvt_pk_bf16_f32 v36, v62, v63
	v_cvt_pk_bf16_f32 v37, v64, v65
	s_waitcnt lgkmcnt(0)
	s_nop 0
	v_mfma_f32_32x32x16_bf16 v[18:33], v[38:41], v[34:37], v[18:33]
	ds_read_b64_tr_b16 v[38:39], v69 offset:25408
	ds_read_b64_tr_b16 v[40:41], v69 offset:26560
	s_waitcnt lgkmcnt(0)
	v_mfma_f32_32x32x16_bf16 v[2:17], v[38:41], v[34:37], v[2:17]
	ds_read_b64_tr_b16 v[38:39], v69 offset:27648
	ds_read_b64_tr_b16 v[40:41], v69 offset:28800
	v_cvt_pk_bf16_f32 v34, v66, v67
	v_cvt_pk_bf16_f32 v35, v70, v71
	v_cvt_pk_bf16_f32 v36, v72, v73
	v_cvt_pk_bf16_f32 v37, v74, v75
	s_waitcnt lgkmcnt(0)
	s_nop 0
	v_mfma_f32_32x32x16_bf16 v[18:33], v[38:41], v[34:37], v[18:33]
	ds_read_b64_tr_b16 v[38:39], v69 offset:27712
	ds_read_b64_tr_b16 v[40:41], v69 offset:28864
	s_waitcnt lgkmcnt(0)
	v_mfma_f32_32x32x16_bf16 v[2:17], v[38:41], v[34:37], v[2:17]
	ds_read_b64_tr_b16 v[38:39], v69 offset:29952
	ds_read_b64_tr_b16 v[40:41], v69 offset:31104
	v_cvt_pk_bf16_f32 v34, v76, v77
	v_cvt_pk_bf16_f32 v35, v78, v79
	v_cvt_pk_bf16_f32 v36, v80, v81
	v_cvt_pk_bf16_f32 v37, v84, v85
	s_waitcnt lgkmcnt(0)
	s_nop 0
	v_mfma_f32_32x32x16_bf16 v[18:33], v[38:41], v[34:37], v[18:33]
	ds_read_b64_tr_b16 v[38:39], v69 offset:30016
	ds_read_b64_tr_b16 v[40:41], v69 offset:31168
	s_waitcnt lgkmcnt(0)
	v_mfma_f32_32x32x16_bf16 v[2:17], v[38:41], v[34:37], v[2:17]
	ds_read_b64_tr_b16 v[38:39], v69 offset:32256
	ds_read_b64_tr_b16 v[40:41], v69 offset:33408
	v_cvt_pk_bf16_f32 v34, v82, v83
	v_cvt_pk_bf16_f32 v35, v86, v87
	v_cvt_pk_bf16_f32 v36, v88, v89
	v_cvt_pk_bf16_f32 v37, v90, v91
	s_waitcnt lgkmcnt(0)
	s_nop 0
	v_mfma_f32_32x32x16_bf16 v[18:33], v[38:41], v[34:37], v[18:33]
	ds_read_b64_tr_b16 v[38:39], v69 offset:32320
	ds_read_b64_tr_b16 v[40:41], v69 offset:33472
	s_waitcnt lgkmcnt(0)
	v_mfma_f32_32x32x16_bf16 v[2:17], v[38:41], v[34:37], v[2:17]
	ds_read_b64_tr_b16 v[38:39], v69 offset:34560
	ds_read_b64_tr_b16 v[40:41], v69 offset:35712
	v_cvt_pk_bf16_f32 v34, v92, v93
	v_cvt_pk_bf16_f32 v35, v94, v95
	v_cvt_pk_bf16_f32 v36, v96, v97
	v_cvt_pk_bf16_f32 v37, v68, v1
	s_waitcnt lgkmcnt(0)
	s_nop 0
	v_mfma_f32_32x32x16_bf16 v[18:33], v[38:41], v[34:37], v[18:33]
	ds_read_b64_tr_b16 v[38:39], v69 offset:34624
	ds_read_b64_tr_b16 v[40:41], v69 offset:35776
	s_waitcnt lgkmcnt(0)
	v_mfma_f32_32x32x16_bf16 v[2:17], v[38:41], v[34:37], v[2:17]

.LBB0_398:
	s_or_b64 exec, exec, s[78:79]
	v_exp_f32_e32 v88, v1
	v_add_u32_e32 v1, s91, v178
	s_nop 0
	s_nop 2
	ds_read_b64_tr_b16 v[52:53], v1 offset:18432
	ds_read_b64_tr_b16 v[54:55], v1 offset:19584
	v_cvt_pk_bf16_f32 v50, v94, v95
	v_pk_add_f32 v[48:49], v[88:89], v[140:141]
	v_cvt_pk_bf16_f32 v51, v130, v131
	v_add_f32_e32 v89, v48, v49
	v_cvt_pk_bf16_f32 v48, v2, v3
	v_cvt_pk_bf16_f32 v49, v12, v13
	v_cvt_pk_bf16_f32 v3, v8, v9
	v_cvt_pk_bf16_f32 v2, v4, v5
	s_waitcnt lgkmcnt(0)
	v_mfma_f32_32x32x16_bf16 v[32:47], v[52:55], v[48:51], v[32:47]
	ds_read_b64_tr_b16 v[52:53], v1 offset:18496
	ds_read_b64_tr_b16 v[54:55], v1 offset:19648
	v_cvt_pk_bf16_f32 v4, v14, v15
	v_cvt_pk_bf16_f32 v5, v136, v137
	s_waitcnt lgkmcnt(0)
	v_mfma_f32_32x32x16_bf16 v[16:31], v[52:55], v[48:51], v[16:31]
	v_cvt_pk_bf16_f32 v49, v10, v11
	ds_read_b64_tr_b16 v[10:11], v1 offset:20736
	ds_read_b64_tr_b16 v[12:13], v1 offset:21888
	v_cvt_pk_bf16_f32 v48, v6, v7
	v_cvt_pk_bf16_f32 v50, v92, v93
	v_cvt_pk_bf16_f32 v51, v128, v129
	s_waitcnt lgkmcnt(0)
	s_nop 0
	v_mfma_f32_32x32x16_bf16 v[32:47], v[10:13], v[48:51], v[32:47]
	ds_read_b64_tr_b16 v[10:11], v1 offset:20800
	ds_read_b64_tr_b16 v[12:13], v1 offset:21952
	ds_read_b64_tr_b16 v[6:7], v1 offset:23040
	ds_read_b64_tr_b16 v[8:9], v1 offset:24192
	s_waitcnt lgkmcnt(2)
	v_mfma_f32_32x32x16_bf16 v[16:31], v[10:13], v[48:51], v[16:31]
	s_waitcnt lgkmcnt(0)
	v_mfma_f32_32x32x16_bf16 v[32:47], v[6:9], v[2:5], v[32:47]
	ds_read_b64_tr_b16 v[6:7], v1 offset:23104
	ds_read_b64_tr_b16 v[8:9], v1 offset:24256
	s_waitcnt lgkmcnt(0)
	v_mfma_f32_32x32x16_bf16 v[16:31], v[6:9], v[2:5], v[16:31]
	ds_read_b64_tr_b16 v[6:7], v1 offset:25344
	ds_read_b64_tr_b16 v[8:9], v1 offset:26496
	v_cvt_pk_bf16_f32 v2, v96, v97
	v_cvt_pk_bf16_f32 v3, v132, v133
	v_cvt_pk_bf16_f32 v4, v134, v135
	v_cvt_pk_bf16_f32 v5, v138, v88
	s_waitcnt lgkmcnt(0)
	s_nop 0
	v_mfma_f32_32x32x16_bf16 v[32:47], v[6:9], v[2:5], v[32:47]
	ds_read_b64_tr_b16 v[6:7], v1 offset:25408
	ds_read_b64_tr_b16 v[8:9], v1 offset:26560
	s_waitcnt lgkmcnt(0)
	v_mfma_f32_32x32x16_bf16 v[16:31], v[6:9], v[2:5], v[16:31]
